# S5 mode-1 item loop: dropped the vmcnt(0) that waited for the 16 epilogue stores before claiming the next item (the prefetched index is already covered by the epilogue's load wait)
# speedup vs baseline: 1.0011x; 1.0008x over previous
.LBB0_639:
	s_or_b64 exec, exec, s[2:3]
	v_readfirstlane_b32 s28, v184
	s_add_i32 s28, s28, 0x100
	s_lshl_b32 s28, s28, 3
	s_add_i32 s28, s28, s29
	s_cmp_ge_u32 s28, s17
	s_cbranch_scc1 .LBB0_654
	v_mov_b32_e32 v105, s28
